# MIX spatial-gating epilogue restructured: all U/gain/bias loads issued up front, counted vmcnt waits, stores no longer waited per row group
# speedup vs baseline: 1.0148x; 1.0148x over previous
.LBB0_238:
	s_or_b64 exec, exec, s[8:9]
	v_cvt_pk_bf16_f32 v2, v9, v8
	v_cvt_pk_bf16_f32 v3, v5, v4
	v_cvt_pk_bf16_f32 v4, v7, v6
	v_cvt_pk_bf16_f32 v5, v1, v0
	ds_write_b128 v115, v[2:5]
	s_waitcnt vmcnt(0)
	s_waitcnt lgkmcnt(0)
	s_barrier
	ds_read_b64_tr_b16 v[0:1], v116
	ds_read_b64_tr_b16 v[2:3], v116 offset:2048
	ds_read_b128 v[4:7], v117
	s_waitcnt lgkmcnt(0)
	v_mfma_f32_32x32x16_bf16 v[48:63], v[0:3], v[4:7], 0
	ds_read_b128 v[4:7], v117 offset:8192
	s_lshl_b32 s8, s1, 1
	s_mov_b32 s9, s5
	v_or_b32_e32 v94, s91, v65
	v_or_b32_e32 v79, s4, v65
	v_ashrrev_i32_e32 v95, 31, v94
	v_lshlrev_b32_e32 v79, 2, v79
	s_waitcnt lgkmcnt(0)
	v_mfma_f32_32x32x16_bf16 v[32:47], v[0:3], v[4:7], 0
	ds_read_b128 v[4:7], v117 offset:16384
	v_lshlrev_b64 v[94:95], 12, v[94:95]
	s_add_i32 s90, s90, s0
	s_add_i32 s85, s85, s92
	s_waitcnt lgkmcnt(0)
	v_mfma_f32_32x32x16_bf16 v[16:31], v[0:3], v[4:7], 0
	ds_read_b128 v[4:7], v117 offset:24576
	ds_read_b64_tr_b16 v[90:91], v116 offset:8192
	ds_read_b64_tr_b16 v[92:93], v116 offset:10240
	ds_read_b128 v[126:129], v118
	s_waitcnt lgkmcnt(0)
	v_mfma_f32_32x32x16_bf16 v[48:63], v[90:93], v[126:129], v[48:63]
	ds_read_b128 v[126:129], v118 offset:8192
	s_waitcnt lgkmcnt(0)
	v_mfma_f32_32x32x16_bf16 v[32:47], v[90:93], v[126:129], v[32:47]
	ds_read_b128 v[126:129], v118 offset:16384
	v_mfma_f32_32x32x16_bf16 v[0:15], v[0:3], v[4:7], 0
	s_waitcnt lgkmcnt(0)
	v_mfma_f32_32x32x16_bf16 v[16:31], v[90:93], v[126:129], v[16:31]
	ds_read_b128 v[126:129], v118 offset:24576
	s_waitcnt lgkmcnt(0)
	v_mfma_f32_32x32x16_bf16 v[0:15], v[90:93], v[126:129], v[0:15]
	ds_read_b64_tr_b16 v[90:91], v116 offset:16384
	ds_read_b64_tr_b16 v[92:93], v116 offset:18432
	ds_read_b128 v[126:129], v119 offset:8192
	s_waitcnt lgkmcnt(0)
	v_mfma_f32_32x32x16_bf16 v[32:47], v[90:93], v[126:129], v[32:47]
	ds_read_b128 v[126:129], v119 offset:16384
	s_waitcnt lgkmcnt(0)
	v_mfma_f32_32x32x16_bf16 v[16:31], v[90:93], v[126:129], v[16:31]
	ds_read_b128 v[126:129], v119 offset:24576
	s_waitcnt lgkmcnt(0)
	v_mfma_f32_32x32x16_bf16 v[0:15], v[90:93], v[126:129], v[0:15]
	ds_read_b64_tr_b16 v[90:91], v116 offset:24576
	ds_read_b64_tr_b16 v[92:93], v116 offset:26624
	ds_read_b128 v[126:129], v120 offset:8192
	s_waitcnt lgkmcnt(0)
	v_mfma_f32_32x32x16_bf16 v[32:47], v[90:93], v[126:129], v[32:47]
	ds_read_b128 v[126:129], v120 offset:16384
	s_waitcnt lgkmcnt(0)
	v_mfma_f32_32x32x16_bf16 v[16:31], v[90:93], v[126:129], v[16:31]
	ds_read_b128 v[126:129], v120 offset:24576
	s_waitcnt lgkmcnt(0)
	v_mfma_f32_32x32x16_bf16 v[0:15], v[90:93], v[126:129], v[0:15]
	ds_read_b64_tr_b16 v[90:91], v116 offset:32768
	ds_read_b64_tr_b16 v[92:93], v116 offset:34816
	ds_read_b128 v[126:129], v121 offset:16384
	s_waitcnt lgkmcnt(0)
	v_mfma_f32_32x32x16_bf16 v[16:31], v[90:93], v[126:129], v[16:31]
	ds_read_b128 v[126:129], v121 offset:24576
	s_waitcnt lgkmcnt(0)
	v_mfma_f32_32x32x16_bf16 v[0:15], v[90:93], v[126:129], v[0:15]
	ds_read_b64_tr_b16 v[90:91], v116 offset:40960
	ds_read_b64_tr_b16 v[92:93], v116 offset:43008
	ds_read_b128 v[126:129], v122 offset:16384
	s_waitcnt lgkmcnt(0)
	v_mfma_f32_32x32x16_bf16 v[16:31], v[90:93], v[126:129], v[16:31]
	ds_read_b128 v[126:129], v122 offset:24576
	s_waitcnt lgkmcnt(0)
	v_mfma_f32_32x32x16_bf16 v[0:15], v[90:93], v[126:129], v[0:15]
	ds_read_b64_tr_b16 v[90:91], v116 offset:49152
	ds_read_b64_tr_b16 v[92:93], v116 offset:51200
	ds_read_b128 v[126:129], v123 offset:24576
	s_waitcnt lgkmcnt(0)
	v_mfma_f32_32x32x16_bf16 v[0:15], v[90:93], v[126:129], v[0:15]
	ds_read_b64_tr_b16 v[90:91], v116 offset:57344
	ds_read_b64_tr_b16 v[92:93], v116 offset:59392
	ds_read_b128 v[126:129], v124 offset:24576
	global_load_dword v79, v79, s[96:97]
	s_waitcnt lgkmcnt(0)
	v_mfma_f32_32x32x16_bf16 v[0:15], v[90:93], v[126:129], v[0:15]
	v_lshl_add_u64 v[92:93], v[72:73], 0, s[8:9]
	s_lshl_b32 s8, s1, 2
	v_lshl_add_u64 v[90:91], v[74:75], 0, s[8:9]
	v_lshl_add_u64 v[94:95], v[92:93], 0, v[94:95]
	s_cmpk_gt_i32 s90, 0x3ff
	global_load_dwordx4 v[136:139], v[90:91], off
	global_load_dwordx4 v[140:143], v[90:91], off offset:32
	global_load_dwordx4 v[144:147], v[90:91], off offset:64
	global_load_dwordx4 v[148:151], v[90:91], off offset:96
	global_load_dwordx2 v[160:161], v[94:95], off
	global_load_dwordx2 v[162:163], v[94:95], off offset:16
	global_load_dwordx2 v[164:165], v[94:95], off offset:32
	global_load_dwordx2 v[166:167], v[94:95], off offset:48
	v_add_lshl_u32 v132, s4, v65, 2
	v_or_b32_e32 v152, s91, v108
	v_ashrrev_i32_e32 v153, 31, v152
	v_lshlrev_b64 v[152:153], 12, v[152:153]
	v_lshl_add_u64 v[152:153], v[92:93], 0, v[152:153]
	global_load_dword v133, v132, s[96:97] offset:128
	global_load_dwordx2 v[168:169], v[152:153], off
	global_load_dwordx2 v[170:171], v[152:153], off offset:16
	global_load_dwordx2 v[172:173], v[152:153], off offset:32
	global_load_dwordx2 v[174:175], v[152:153], off offset:48
	v_or_b32_e32 v154, s91, v109
	v_ashrrev_i32_e32 v155, 31, v154
	v_lshlrev_b64 v[154:155], 12, v[154:155]
	v_lshl_add_u64 v[154:155], v[92:93], 0, v[154:155]
	global_load_dword v134, v132, s[96:97] offset:256
	global_load_dwordx2 v[176:177], v[154:155], off
	global_load_dwordx2 v[178:179], v[154:155], off offset:16
	global_load_dwordx2 v[180:181], v[154:155], off offset:32
	global_load_dwordx2 v[182:183], v[154:155], off offset:48
	v_or_b32_e32 v156, s91, v110
	v_ashrrev_i32_e32 v157, 31, v156
	v_lshlrev_b64 v[156:157], 12, v[156:157]
	v_lshl_add_u64 v[156:157], v[92:93], 0, v[156:157]
	global_load_dword v135, v132, s[96:97] offset:384
	global_load_dwordx2 v[184:185], v[156:157], off
	global_load_dwordx2 v[186:187], v[156:157], off offset:16
	global_load_dwordx2 v[188:189], v[156:157], off offset:32
	global_load_dwordx2 v[190:191], v[156:157], off offset:48
	s_waitcnt vmcnt(15)
	v_fma_f32 v48, v48, v136, v79
	v_lshlrev_b32_e32 v192, 16, v160
	v_and_b32_e32 v193, 0xffff0000, v160
	v_fma_f32 v49, v49, v137, v79
	v_mul_f32_e32 v48, v48, v192
	v_mul_f32_e32 v49, v49, v193
	v_lshlrev_b32_e32 v194, 16, v161
	v_and_b32_e32 v195, 0xffff0000, v161
	v_fma_f32 v50, v50, v138, v79
	v_fma_f32 v51, v51, v139, v79
	v_mul_f32_e32 v50, v50, v194
	v_mul_f32_e32 v51, v51, v195
	v_cvt_pk_bf16_f32 v48, v48, v49
	v_cvt_pk_bf16_f32 v49, v50, v51
	global_store_dwordx2 v[94:95], v[48:49], off
	v_fma_f32 v52, v52, v140, v79
	v_lshlrev_b32_e32 v192, 16, v162
	v_and_b32_e32 v193, 0xffff0000, v162
	v_fma_f32 v53, v53, v141, v79
	v_mul_f32_e32 v52, v52, v192
	v_mul_f32_e32 v53, v53, v193
	v_lshlrev_b32_e32 v194, 16, v163
	v_and_b32_e32 v195, 0xffff0000, v163
	v_fma_f32 v54, v54, v142, v79
	v_fma_f32 v55, v55, v143, v79
	v_mul_f32_e32 v54, v54, v194
	v_mul_f32_e32 v55, v55, v195
	v_cvt_pk_bf16_f32 v52, v52, v53
	v_cvt_pk_bf16_f32 v53, v54, v55
	global_store_dwordx2 v[94:95], v[52:53], off offset:16
	v_fma_f32 v56, v56, v144, v79
	v_lshlrev_b32_e32 v192, 16, v164
	v_and_b32_e32 v193, 0xffff0000, v164
	v_fma_f32 v57, v57, v145, v79
	v_mul_f32_e32 v56, v56, v192
	v_mul_f32_e32 v57, v57, v193
	v_lshlrev_b32_e32 v194, 16, v165
	v_and_b32_e32 v195, 0xffff0000, v165
	v_fma_f32 v58, v58, v146, v79
	v_fma_f32 v59, v59, v147, v79
	v_mul_f32_e32 v58, v58, v194
	v_mul_f32_e32 v59, v59, v195
	v_cvt_pk_bf16_f32 v56, v56, v57
	v_cvt_pk_bf16_f32 v57, v58, v59
	global_store_dwordx2 v[94:95], v[56:57], off offset:32
	v_fma_f32 v60, v60, v148, v79
	v_lshlrev_b32_e32 v192, 16, v166
	v_and_b32_e32 v193, 0xffff0000, v166
	v_fma_f32 v61, v61, v149, v79
	v_mul_f32_e32 v60, v60, v192
	v_mul_f32_e32 v61, v61, v193
	v_lshlrev_b32_e32 v194, 16, v167
	v_and_b32_e32 v195, 0xffff0000, v167
	v_fma_f32 v62, v62, v150, v79
	v_fma_f32 v63, v63, v151, v79
	v_mul_f32_e32 v62, v62, v194
	v_mul_f32_e32 v63, v63, v195
	v_cvt_pk_bf16_f32 v60, v60, v61
	v_cvt_pk_bf16_f32 v61, v62, v63
	global_store_dwordx2 v[94:95], v[60:61], off offset:48
	s_waitcnt vmcnt(14)
	v_fma_f32 v32, v32, v136, v133
	v_lshlrev_b32_e32 v192, 16, v168
	v_and_b32_e32 v193, 0xffff0000, v168
	v_fma_f32 v33, v33, v137, v133
	v_mul_f32_e32 v32, v32, v192
	v_mul_f32_e32 v33, v33, v193
	v_lshlrev_b32_e32 v194, 16, v169
	v_and_b32_e32 v195, 0xffff0000, v169
	v_fma_f32 v34, v34, v138, v133
	v_fma_f32 v35, v35, v139, v133
	v_mul_f32_e32 v34, v34, v194
	v_mul_f32_e32 v35, v35, v195
	v_cvt_pk_bf16_f32 v32, v32, v33
	v_cvt_pk_bf16_f32 v33, v34, v35
	global_store_dwordx2 v[152:153], v[32:33], off
	v_fma_f32 v36, v36, v140, v133
	v_lshlrev_b32_e32 v192, 16, v170
	v_and_b32_e32 v193, 0xffff0000, v170
	v_fma_f32 v37, v37, v141, v133
	v_mul_f32_e32 v36, v36, v192
	v_mul_f32_e32 v37, v37, v193
	v_lshlrev_b32_e32 v194, 16, v171
	v_and_b32_e32 v195, 0xffff0000, v171
	v_fma_f32 v38, v38, v142, v133
	v_fma_f32 v39, v39, v143, v133
	v_mul_f32_e32 v38, v38, v194
	v_mul_f32_e32 v39, v39, v195
	v_cvt_pk_bf16_f32 v36, v36, v37
	v_cvt_pk_bf16_f32 v37, v38, v39
	global_store_dwordx2 v[152:153], v[36:37], off offset:16
	v_fma_f32 v40, v40, v144, v133
	v_lshlrev_b32_e32 v192, 16, v172
	v_and_b32_e32 v193, 0xffff0000, v172
	v_fma_f32 v41, v41, v145, v133
	v_mul_f32_e32 v40, v40, v192
	v_mul_f32_e32 v41, v41, v193
	v_lshlrev_b32_e32 v194, 16, v173
	v_and_b32_e32 v195, 0xffff0000, v173
	v_fma_f32 v42, v42, v146, v133
	v_fma_f32 v43, v43, v147, v133
	v_mul_f32_e32 v42, v42, v194
	v_mul_f32_e32 v43, v43, v195
	v_cvt_pk_bf16_f32 v40, v40, v41
	v_cvt_pk_bf16_f32 v41, v42, v43
	global_store_dwordx2 v[152:153], v[40:41], off offset:32
	v_fma_f32 v44, v44, v148, v133
	v_lshlrev_b32_e32 v192, 16, v174
	v_and_b32_e32 v193, 0xffff0000, v174
	v_fma_f32 v45, v45, v149, v133
	v_mul_f32_e32 v44, v44, v192
	v_mul_f32_e32 v45, v45, v193
	v_lshlrev_b32_e32 v194, 16, v175
	v_and_b32_e32 v195, 0xffff0000, v175
	v_fma_f32 v46, v46, v150, v133
	v_fma_f32 v47, v47, v151, v133
	v_mul_f32_e32 v46, v46, v194
	v_mul_f32_e32 v47, v47, v195
	v_cvt_pk_bf16_f32 v44, v44, v45
	v_cvt_pk_bf16_f32 v45, v46, v47
	global_store_dwordx2 v[152:153], v[44:45], off offset:48
	s_waitcnt vmcnt(13)
	v_fma_f32 v16, v16, v136, v134
	v_lshlrev_b32_e32 v192, 16, v176
	v_and_b32_e32 v193, 0xffff0000, v176
	v_fma_f32 v17, v17, v137, v134
	v_mul_f32_e32 v16, v16, v192
	v_mul_f32_e32 v17, v17, v193
	v_lshlrev_b32_e32 v194, 16, v177
	v_and_b32_e32 v195, 0xffff0000, v177
	v_fma_f32 v18, v18, v138, v134
	v_fma_f32 v19, v19, v139, v134
	v_mul_f32_e32 v18, v18, v194
	v_mul_f32_e32 v19, v19, v195
	v_cvt_pk_bf16_f32 v16, v16, v17
	v_cvt_pk_bf16_f32 v17, v18, v19
	global_store_dwordx2 v[154:155], v[16:17], off
	v_fma_f32 v20, v20, v140, v134
	v_lshlrev_b32_e32 v192, 16, v178
	v_and_b32_e32 v193, 0xffff0000, v178
	v_fma_f32 v21, v21, v141, v134
	v_mul_f32_e32 v20, v20, v192
	v_mul_f32_e32 v21, v21, v193
	v_lshlrev_b32_e32 v194, 16, v179
	v_and_b32_e32 v195, 0xffff0000, v179
	v_fma_f32 v22, v22, v142, v134
	v_fma_f32 v23, v23, v143, v134
	v_mul_f32_e32 v22, v22, v194
	v_mul_f32_e32 v23, v23, v195
	v_cvt_pk_bf16_f32 v20, v20, v21
	v_cvt_pk_bf16_f32 v21, v22, v23
	global_store_dwordx2 v[154:155], v[20:21], off offset:16
	v_fma_f32 v24, v24, v144, v134
	v_lshlrev_b32_e32 v192, 16, v180
	v_and_b32_e32 v193, 0xffff0000, v180
	v_fma_f32 v25, v25, v145, v134
	v_mul_f32_e32 v24, v24, v192
	v_mul_f32_e32 v25, v25, v193
	v_lshlrev_b32_e32 v194, 16, v181
	v_and_b32_e32 v195, 0xffff0000, v181
	v_fma_f32 v26, v26, v146, v134
	v_fma_f32 v27, v27, v147, v134
	v_mul_f32_e32 v26, v26, v194
	v_mul_f32_e32 v27, v27, v195
	v_cvt_pk_bf16_f32 v24, v24, v25
	v_cvt_pk_bf16_f32 v25, v26, v27
	global_store_dwordx2 v[154:155], v[24:25], off offset:32
	v_fma_f32 v28, v28, v148, v134
	v_lshlrev_b32_e32 v192, 16, v182
	v_and_b32_e32 v193, 0xffff0000, v182
	v_fma_f32 v29, v29, v149, v134
	v_mul_f32_e32 v28, v28, v192
	v_mul_f32_e32 v29, v29, v193
	v_lshlrev_b32_e32 v194, 16, v183
	v_and_b32_e32 v195, 0xffff0000, v183
	v_fma_f32 v30, v30, v150, v134
	v_fma_f32 v31, v31, v151, v134
	v_mul_f32_e32 v30, v30, v194
	v_mul_f32_e32 v31, v31, v195
	v_cvt_pk_bf16_f32 v28, v28, v29
	v_cvt_pk_bf16_f32 v29, v30, v31
	global_store_dwordx2 v[154:155], v[28:29], off offset:48
	s_waitcnt vmcnt(12)
	v_fma_f32 v0, v0, v136, v135
	v_lshlrev_b32_e32 v192, 16, v184
	v_and_b32_e32 v193, 0xffff0000, v184
	v_fma_f32 v1, v1, v137, v135
	v_mul_f32_e32 v0, v0, v192
	v_mul_f32_e32 v1, v1, v193
	v_lshlrev_b32_e32 v194, 16, v185
	v_and_b32_e32 v195, 0xffff0000, v185
	v_fma_f32 v2, v2, v138, v135
	v_fma_f32 v3, v3, v139, v135
	v_mul_f32_e32 v2, v2, v194
	v_mul_f32_e32 v3, v3, v195
	v_cvt_pk_bf16_f32 v0, v0, v1
	v_cvt_pk_bf16_f32 v1, v2, v3
	global_store_dwordx2 v[156:157], v[0:1], off
	v_fma_f32 v4, v4, v140, v135
	v_lshlrev_b32_e32 v192, 16, v186
	v_and_b32_e32 v193, 0xffff0000, v186
	v_fma_f32 v5, v5, v141, v135
	v_mul_f32_e32 v4, v4, v192
	v_mul_f32_e32 v5, v5, v193
	v_lshlrev_b32_e32 v194, 16, v187
	v_and_b32_e32 v195, 0xffff0000, v187
	v_fma_f32 v6, v6, v142, v135
	v_fma_f32 v7, v7, v143, v135
	v_mul_f32_e32 v6, v6, v194
	v_mul_f32_e32 v7, v7, v195
	v_cvt_pk_bf16_f32 v4, v4, v5
	v_cvt_pk_bf16_f32 v5, v6, v7
	global_store_dwordx2 v[156:157], v[4:5], off offset:16
	v_fma_f32 v8, v8, v144, v135
	v_lshlrev_b32_e32 v192, 16, v188
	v_and_b32_e32 v193, 0xffff0000, v188
	v_fma_f32 v9, v9, v145, v135
	v_mul_f32_e32 v8, v8, v192
	v_mul_f32_e32 v9, v9, v193
	v_lshlrev_b32_e32 v194, 16, v189
	v_and_b32_e32 v195, 0xffff0000, v189
	v_fma_f32 v10, v10, v146, v135
	v_fma_f32 v11, v11, v147, v135
	v_mul_f32_e32 v10, v10, v194
	v_mul_f32_e32 v11, v11, v195
	v_cvt_pk_bf16_f32 v8, v8, v9
	v_cvt_pk_bf16_f32 v9, v10, v11
	global_store_dwordx2 v[156:157], v[8:9], off offset:32
	v_fma_f32 v12, v12, v148, v135
	v_lshlrev_b32_e32 v192, 16, v190
	v_and_b32_e32 v193, 0xffff0000, v190
	v_fma_f32 v13, v13, v149, v135
	v_mul_f32_e32 v12, v12, v192
	v_mul_f32_e32 v13, v13, v193
	v_lshlrev_b32_e32 v194, 16, v191
	v_and_b32_e32 v195, 0xffff0000, v191
	v_fma_f32 v14, v14, v150, v135
	v_fma_f32 v15, v15, v151, v135
	v_mul_f32_e32 v14, v14, v194
	v_mul_f32_e32 v15, v15, v195
	v_cvt_pk_bf16_f32 v12, v12, v13
	v_cvt_pk_bf16_f32 v13, v14, v15
	global_store_dwordx2 v[156:157], v[12:13], off offset:48
	s_barrier
	s_cbranch_scc1 .LBB0_305

.LBB0_994:
	s_or_b64 exec, exec, s[78:79]
	v_cvt_pk_bf16_f32 v2, v9, v8
	v_cvt_pk_bf16_f32 v3, v5, v4
	v_cvt_pk_bf16_f32 v4, v7, v6
	v_cvt_pk_bf16_f32 v5, v1, v0
	ds_write_b128 v115, v[2:5]
	s_waitcnt vmcnt(0)
	s_waitcnt lgkmcnt(0)
	s_barrier
	ds_read_b64_tr_b16 v[0:1], v116
	ds_read_b64_tr_b16 v[2:3], v116 offset:2048
	ds_read_b128 v[4:7], v117
	s_waitcnt lgkmcnt(0)
	v_mfma_f32_32x32x16_bf16 v[48:63], v[0:3], v[4:7], 0
	ds_read_b128 v[4:7], v117 offset:8192
	s_lshl_b32 s78, s1, 1
	s_mov_b32 s79, s5
	v_or_b32_e32 v94, s90, v65
	v_or_b32_e32 v79, s4, v65
	v_ashrrev_i32_e32 v95, 31, v94
	v_lshlrev_b32_e32 v79, 2, v79
	s_waitcnt lgkmcnt(0)
	v_mfma_f32_32x32x16_bf16 v[32:47], v[0:3], v[4:7], 0
	ds_read_b128 v[4:7], v117 offset:16384
	v_lshlrev_b64 v[94:95], 12, v[94:95]
	s_add_i32 s93, s93, s0
	s_add_i32 s85, s85, s94
	s_waitcnt lgkmcnt(0)
	v_mfma_f32_32x32x16_bf16 v[16:31], v[0:3], v[4:7], 0
	ds_read_b128 v[4:7], v117 offset:24576
	ds_read_b64_tr_b16 v[90:91], v116 offset:8192
	ds_read_b64_tr_b16 v[92:93], v116 offset:10240
	ds_read_b128 v[126:129], v118
	s_waitcnt lgkmcnt(0)
	v_mfma_f32_32x32x16_bf16 v[48:63], v[90:93], v[126:129], v[48:63]
	ds_read_b128 v[126:129], v118 offset:8192
	s_waitcnt lgkmcnt(0)
	v_mfma_f32_32x32x16_bf16 v[32:47], v[90:93], v[126:129], v[32:47]
	ds_read_b128 v[126:129], v118 offset:16384
	v_mfma_f32_32x32x16_bf16 v[0:15], v[0:3], v[4:7], 0
	s_waitcnt lgkmcnt(0)
	v_mfma_f32_32x32x16_bf16 v[16:31], v[90:93], v[126:129], v[16:31]
	ds_read_b128 v[126:129], v118 offset:24576
	s_waitcnt lgkmcnt(0)
	v_mfma_f32_32x32x16_bf16 v[0:15], v[90:93], v[126:129], v[0:15]
	ds_read_b64_tr_b16 v[90:91], v116 offset:16384
	ds_read_b64_tr_b16 v[92:93], v116 offset:18432
	ds_read_b128 v[126:129], v119 offset:8192
	s_waitcnt lgkmcnt(0)
	v_mfma_f32_32x32x16_bf16 v[32:47], v[90:93], v[126:129], v[32:47]
	ds_read_b128 v[126:129], v119 offset:16384
	s_waitcnt lgkmcnt(0)
	v_mfma_f32_32x32x16_bf16 v[16:31], v[90:93], v[126:129], v[16:31]
	ds_read_b128 v[126:129], v119 offset:24576
	s_waitcnt lgkmcnt(0)
	v_mfma_f32_32x32x16_bf16 v[0:15], v[90:93], v[126:129], v[0:15]
	ds_read_b64_tr_b16 v[90:91], v116 offset:24576
	ds_read_b64_tr_b16 v[92:93], v116 offset:26624
	ds_read_b128 v[126:129], v120 offset:8192
	s_waitcnt lgkmcnt(0)
	v_mfma_f32_32x32x16_bf16 v[32:47], v[90:93], v[126:129], v[32:47]
	ds_read_b128 v[126:129], v120 offset:16384
	s_waitcnt lgkmcnt(0)
	v_mfma_f32_32x32x16_bf16 v[16:31], v[90:93], v[126:129], v[16:31]
	ds_read_b128 v[126:129], v120 offset:24576
	s_waitcnt lgkmcnt(0)
	v_mfma_f32_32x32x16_bf16 v[0:15], v[90:93], v[126:129], v[0:15]
	ds_read_b64_tr_b16 v[90:91], v116 offset:32768
	ds_read_b64_tr_b16 v[92:93], v116 offset:34816
	ds_read_b128 v[126:129], v121 offset:16384
	s_waitcnt lgkmcnt(0)
	v_mfma_f32_32x32x16_bf16 v[16:31], v[90:93], v[126:129], v[16:31]
	ds_read_b128 v[126:129], v121 offset:24576
	s_waitcnt lgkmcnt(0)
	v_mfma_f32_32x32x16_bf16 v[0:15], v[90:93], v[126:129], v[0:15]
	ds_read_b64_tr_b16 v[90:91], v116 offset:40960
	ds_read_b64_tr_b16 v[92:93], v116 offset:43008
	ds_read_b128 v[126:129], v122 offset:16384
	s_waitcnt lgkmcnt(0)
	v_mfma_f32_32x32x16_bf16 v[16:31], v[90:93], v[126:129], v[16:31]
	ds_read_b128 v[126:129], v122 offset:24576
	s_waitcnt lgkmcnt(0)
	v_mfma_f32_32x32x16_bf16 v[0:15], v[90:93], v[126:129], v[0:15]
	ds_read_b64_tr_b16 v[90:91], v116 offset:49152
	ds_read_b64_tr_b16 v[92:93], v116 offset:51200
	ds_read_b128 v[126:129], v123 offset:24576
	s_waitcnt lgkmcnt(0)
	v_mfma_f32_32x32x16_bf16 v[0:15], v[90:93], v[126:129], v[0:15]
	ds_read_b64_tr_b16 v[90:91], v116 offset:57344
	ds_read_b64_tr_b16 v[92:93], v116 offset:59392
	ds_read_b128 v[126:129], v124 offset:24576
	global_load_dword v79, v79, s[8:9]
	s_waitcnt lgkmcnt(0)
	v_mfma_f32_32x32x16_bf16 v[0:15], v[90:93], v[126:129], v[0:15]
	v_lshl_add_u64 v[92:93], v[72:73], 0, s[78:79]
	s_lshl_b32 s78, s1, 2
	v_lshl_add_u64 v[90:91], v[74:75], 0, s[78:79]
	v_lshl_add_u64 v[94:95], v[92:93], 0, v[94:95]
	s_cmpk_gt_i32 s93, 0x3ff
	global_load_dwordx4 v[136:139], v[90:91], off
	global_load_dwordx4 v[140:143], v[90:91], off offset:32
	global_load_dwordx4 v[144:147], v[90:91], off offset:64
	global_load_dwordx4 v[148:151], v[90:91], off offset:96
	global_load_dwordx2 v[160:161], v[94:95], off
	global_load_dwordx2 v[162:163], v[94:95], off offset:16
	global_load_dwordx2 v[164:165], v[94:95], off offset:32
	global_load_dwordx2 v[166:167], v[94:95], off offset:48
	v_or_b32_e32 v152, s90, v108
	v_ashrrev_i32_e32 v153, 31, v152
	v_lshlrev_b64 v[152:153], 12, v[152:153]
	v_lshl_add_u64 v[152:153], v[92:93], 0, v[152:153]
	v_or_b32_e32 v132, s4, v108
	v_lshlrev_b32_e32 v132, 2, v132
	global_load_dword v133, v132, s[8:9]
	global_load_dwordx2 v[168:169], v[152:153], off
	global_load_dwordx2 v[170:171], v[152:153], off offset:16
	global_load_dwordx2 v[172:173], v[152:153], off offset:32
	global_load_dwordx2 v[174:175], v[152:153], off offset:48
	v_or_b32_e32 v154, s90, v109
	v_ashrrev_i32_e32 v155, 31, v154
	v_lshlrev_b64 v[154:155], 12, v[154:155]
	v_lshl_add_u64 v[154:155], v[92:93], 0, v[154:155]
	v_or_b32_e32 v132, s4, v109
	v_lshlrev_b32_e32 v132, 2, v132
	global_load_dword v134, v132, s[8:9]
	global_load_dwordx2 v[176:177], v[154:155], off
	global_load_dwordx2 v[178:179], v[154:155], off offset:16
	global_load_dwordx2 v[180:181], v[154:155], off offset:32
	global_load_dwordx2 v[182:183], v[154:155], off offset:48
	v_or_b32_e32 v156, s90, v110
	v_ashrrev_i32_e32 v157, 31, v156
	v_lshlrev_b64 v[156:157], 12, v[156:157]
	v_lshl_add_u64 v[156:157], v[92:93], 0, v[156:157]
	v_or_b32_e32 v132, s4, v110
	v_lshlrev_b32_e32 v132, 2, v132
	global_load_dword v135, v132, s[8:9]
	global_load_dwordx2 v[184:185], v[156:157], off
	global_load_dwordx2 v[186:187], v[156:157], off offset:16
	global_load_dwordx2 v[188:189], v[156:157], off offset:32
	global_load_dwordx2 v[190:191], v[156:157], off offset:48
	s_waitcnt vmcnt(15)
	v_fma_f32 v48, v48, v136, v79
	v_lshlrev_b32_e32 v192, 16, v160
	v_and_b32_e32 v193, 0xffff0000, v160
	v_fma_f32 v49, v49, v137, v79
	v_mul_f32_e32 v48, v48, v192
	v_mul_f32_e32 v49, v49, v193
	v_lshlrev_b32_e32 v194, 16, v161
	v_and_b32_e32 v195, 0xffff0000, v161
	v_fma_f32 v50, v50, v138, v79
	v_fma_f32 v51, v51, v139, v79
	v_mul_f32_e32 v50, v50, v194
	v_mul_f32_e32 v51, v51, v195
	v_cvt_pk_bf16_f32 v48, v48, v49
	v_cvt_pk_bf16_f32 v49, v50, v51
	global_store_dwordx2 v[94:95], v[48:49], off
	v_fma_f32 v52, v52, v140, v79
	v_lshlrev_b32_e32 v192, 16, v162
	v_and_b32_e32 v193, 0xffff0000, v162
	v_fma_f32 v53, v53, v141, v79
	v_mul_f32_e32 v52, v52, v192
	v_mul_f32_e32 v53, v53, v193
	v_lshlrev_b32_e32 v194, 16, v163
	v_and_b32_e32 v195, 0xffff0000, v163
	v_fma_f32 v54, v54, v142, v79
	v_fma_f32 v55, v55, v143, v79
	v_mul_f32_e32 v54, v54, v194
	v_mul_f32_e32 v55, v55, v195
	v_cvt_pk_bf16_f32 v52, v52, v53
	v_cvt_pk_bf16_f32 v53, v54, v55
	global_store_dwordx2 v[94:95], v[52:53], off offset:16
	v_fma_f32 v56, v56, v144, v79
	v_lshlrev_b32_e32 v192, 16, v164
	v_and_b32_e32 v193, 0xffff0000, v164
	v_fma_f32 v57, v57, v145, v79
	v_mul_f32_e32 v56, v56, v192
	v_mul_f32_e32 v57, v57, v193
	v_lshlrev_b32_e32 v194, 16, v165
	v_and_b32_e32 v195, 0xffff0000, v165
	v_fma_f32 v58, v58, v146, v79
	v_fma_f32 v59, v59, v147, v79
	v_mul_f32_e32 v58, v58, v194
	v_mul_f32_e32 v59, v59, v195
	v_cvt_pk_bf16_f32 v56, v56, v57
	v_cvt_pk_bf16_f32 v57, v58, v59
	global_store_dwordx2 v[94:95], v[56:57], off offset:32
	v_fma_f32 v60, v60, v148, v79
	v_lshlrev_b32_e32 v192, 16, v166
	v_and_b32_e32 v193, 0xffff0000, v166
	v_fma_f32 v61, v61, v149, v79
	v_mul_f32_e32 v60, v60, v192
	v_mul_f32_e32 v61, v61, v193
	v_lshlrev_b32_e32 v194, 16, v167
	v_and_b32_e32 v195, 0xffff0000, v167
	v_fma_f32 v62, v62, v150, v79
	v_fma_f32 v63, v63, v151, v79
	v_mul_f32_e32 v62, v62, v194
	v_mul_f32_e32 v63, v63, v195
	v_cvt_pk_bf16_f32 v60, v60, v61
	v_cvt_pk_bf16_f32 v61, v62, v63
	global_store_dwordx2 v[94:95], v[60:61], off offset:48
	s_waitcnt vmcnt(14)
	v_fma_f32 v32, v32, v136, v133
	v_lshlrev_b32_e32 v192, 16, v168
	v_and_b32_e32 v193, 0xffff0000, v168
	v_fma_f32 v33, v33, v137, v133
	v_mul_f32_e32 v32, v32, v192
	v_mul_f32_e32 v33, v33, v193
	v_lshlrev_b32_e32 v194, 16, v169
	v_and_b32_e32 v195, 0xffff0000, v169
	v_fma_f32 v34, v34, v138, v133
	v_fma_f32 v35, v35, v139, v133
	v_mul_f32_e32 v34, v34, v194
	v_mul_f32_e32 v35, v35, v195
	v_cvt_pk_bf16_f32 v32, v32, v33
	v_cvt_pk_bf16_f32 v33, v34, v35
	global_store_dwordx2 v[152:153], v[32:33], off
	v_fma_f32 v36, v36, v140, v133
	v_lshlrev_b32_e32 v192, 16, v170
	v_and_b32_e32 v193, 0xffff0000, v170
	v_fma_f32 v37, v37, v141, v133
	v_mul_f32_e32 v36, v36, v192
	v_mul_f32_e32 v37, v37, v193
	v_lshlrev_b32_e32 v194, 16, v171
	v_and_b32_e32 v195, 0xffff0000, v171
	v_fma_f32 v38, v38, v142, v133
	v_fma_f32 v39, v39, v143, v133
	v_mul_f32_e32 v38, v38, v194
	v_mul_f32_e32 v39, v39, v195
	v_cvt_pk_bf16_f32 v36, v36, v37
	v_cvt_pk_bf16_f32 v37, v38, v39
	global_store_dwordx2 v[152:153], v[36:37], off offset:16
	v_fma_f32 v40, v40, v144, v133
	v_lshlrev_b32_e32 v192, 16, v172
	v_and_b32_e32 v193, 0xffff0000, v172
	v_fma_f32 v41, v41, v145, v133
	v_mul_f32_e32 v40, v40, v192
	v_mul_f32_e32 v41, v41, v193
	v_lshlrev_b32_e32 v194, 16, v173
	v_and_b32_e32 v195, 0xffff0000, v173
	v_fma_f32 v42, v42, v146, v133
	v_fma_f32 v43, v43, v147, v133
	v_mul_f32_e32 v42, v42, v194
	v_mul_f32_e32 v43, v43, v195
	v_cvt_pk_bf16_f32 v40, v40, v41
	v_cvt_pk_bf16_f32 v41, v42, v43
	global_store_dwordx2 v[152:153], v[40:41], off offset:32
	v_fma_f32 v44, v44, v148, v133
	v_lshlrev_b32_e32 v192, 16, v174
	v_and_b32_e32 v193, 0xffff0000, v174
	v_fma_f32 v45, v45, v149, v133
	v_mul_f32_e32 v44, v44, v192
	v_mul_f32_e32 v45, v45, v193
	v_lshlrev_b32_e32 v194, 16, v175
	v_and_b32_e32 v195, 0xffff0000, v175
	v_fma_f32 v46, v46, v150, v133
	v_fma_f32 v47, v47, v151, v133
	v_mul_f32_e32 v46, v46, v194
	v_mul_f32_e32 v47, v47, v195
	v_cvt_pk_bf16_f32 v44, v44, v45
	v_cvt_pk_bf16_f32 v45, v46, v47
	global_store_dwordx2 v[152:153], v[44:45], off offset:48
	s_waitcnt vmcnt(13)
	v_fma_f32 v16, v16, v136, v134
	v_lshlrev_b32_e32 v192, 16, v176
	v_and_b32_e32 v193, 0xffff0000, v176
	v_fma_f32 v17, v17, v137, v134
	v_mul_f32_e32 v16, v16, v192
	v_mul_f32_e32 v17, v17, v193
	v_lshlrev_b32_e32 v194, 16, v177
	v_and_b32_e32 v195, 0xffff0000, v177
	v_fma_f32 v18, v18, v138, v134
	v_fma_f32 v19, v19, v139, v134
	v_mul_f32_e32 v18, v18, v194
	v_mul_f32_e32 v19, v19, v195
	v_cvt_pk_bf16_f32 v16, v16, v17
	v_cvt_pk_bf16_f32 v17, v18, v19
	global_store_dwordx2 v[154:155], v[16:17], off
	v_fma_f32 v20, v20, v140, v134
	v_lshlrev_b32_e32 v192, 16, v178
	v_and_b32_e32 v193, 0xffff0000, v178
	v_fma_f32 v21, v21, v141, v134
	v_mul_f32_e32 v20, v20, v192
	v_mul_f32_e32 v21, v21, v193
	v_lshlrev_b32_e32 v194, 16, v179
	v_and_b32_e32 v195, 0xffff0000, v179
	v_fma_f32 v22, v22, v142, v134
	v_fma_f32 v23, v23, v143, v134
	v_mul_f32_e32 v22, v22, v194
	v_mul_f32_e32 v23, v23, v195
	v_cvt_pk_bf16_f32 v20, v20, v21
	v_cvt_pk_bf16_f32 v21, v22, v23
	global_store_dwordx2 v[154:155], v[20:21], off offset:16
	v_fma_f32 v24, v24, v144, v134
	v_lshlrev_b32_e32 v192, 16, v180
	v_and_b32_e32 v193, 0xffff0000, v180
	v_fma_f32 v25, v25, v145, v134
	v_mul_f32_e32 v24, v24, v192
	v_mul_f32_e32 v25, v25, v193
	v_lshlrev_b32_e32 v194, 16, v181
	v_and_b32_e32 v195, 0xffff0000, v181
	v_fma_f32 v26, v26, v146, v134
	v_fma_f32 v27, v27, v147, v134
	v_mul_f32_e32 v26, v26, v194
	v_mul_f32_e32 v27, v27, v195
	v_cvt_pk_bf16_f32 v24, v24, v25
	v_cvt_pk_bf16_f32 v25, v26, v27
	global_store_dwordx2 v[154:155], v[24:25], off offset:32
	v_fma_f32 v28, v28, v148, v134
	v_lshlrev_b32_e32 v192, 16, v182
	v_and_b32_e32 v193, 0xffff0000, v182
	v_fma_f32 v29, v29, v149, v134
	v_mul_f32_e32 v28, v28, v192
	v_mul_f32_e32 v29, v29, v193
	v_lshlrev_b32_e32 v194, 16, v183
	v_and_b32_e32 v195, 0xffff0000, v183
	v_fma_f32 v30, v30, v150, v134
	v_fma_f32 v31, v31, v151, v134
	v_mul_f32_e32 v30, v30, v194
	v_mul_f32_e32 v31, v31, v195
	v_cvt_pk_bf16_f32 v28, v28, v29
	v_cvt_pk_bf16_f32 v29, v30, v31
	global_store_dwordx2 v[154:155], v[28:29], off offset:48
	s_waitcnt vmcnt(12)
	v_fma_f32 v0, v0, v136, v135
	v_lshlrev_b32_e32 v192, 16, v184
	v_and_b32_e32 v193, 0xffff0000, v184
	v_fma_f32 v1, v1, v137, v135
	v_mul_f32_e32 v0, v0, v192
	v_mul_f32_e32 v1, v1, v193
	v_lshlrev_b32_e32 v194, 16, v185
	v_and_b32_e32 v195, 0xffff0000, v185
	v_fma_f32 v2, v2, v138, v135
	v_fma_f32 v3, v3, v139, v135
	v_mul_f32_e32 v2, v2, v194
	v_mul_f32_e32 v3, v3, v195
	v_cvt_pk_bf16_f32 v0, v0, v1
	v_cvt_pk_bf16_f32 v1, v2, v3
	global_store_dwordx2 v[156:157], v[0:1], off
	v_fma_f32 v4, v4, v140, v135
	v_lshlrev_b32_e32 v192, 16, v186
	v_and_b32_e32 v193, 0xffff0000, v186
	v_fma_f32 v5, v5, v141, v135
	v_mul_f32_e32 v4, v4, v192
	v_mul_f32_e32 v5, v5, v193
	v_lshlrev_b32_e32 v194, 16, v187
	v_and_b32_e32 v195, 0xffff0000, v187
	v_fma_f32 v6, v6, v142, v135
	v_fma_f32 v7, v7, v143, v135
	v_mul_f32_e32 v6, v6, v194
	v_mul_f32_e32 v7, v7, v195
	v_cvt_pk_bf16_f32 v4, v4, v5
	v_cvt_pk_bf16_f32 v5, v6, v7
	global_store_dwordx2 v[156:157], v[4:5], off offset:16
	v_fma_f32 v8, v8, v144, v135
	v_lshlrev_b32_e32 v192, 16, v188
	v_and_b32_e32 v193, 0xffff0000, v188
	v_fma_f32 v9, v9, v145, v135
	v_mul_f32_e32 v8, v8, v192
	v_mul_f32_e32 v9, v9, v193
	v_lshlrev_b32_e32 v194, 16, v189
	v_and_b32_e32 v195, 0xffff0000, v189
	v_fma_f32 v10, v10, v146, v135
	v_fma_f32 v11, v11, v147, v135
	v_mul_f32_e32 v10, v10, v194
	v_mul_f32_e32 v11, v11, v195
	v_cvt_pk_bf16_f32 v8, v8, v9
	v_cvt_pk_bf16_f32 v9, v10, v11
	global_store_dwordx2 v[156:157], v[8:9], off offset:32
	v_fma_f32 v12, v12, v148, v135
	v_lshlrev_b32_e32 v192, 16, v190
	v_and_b32_e32 v193, 0xffff0000, v190
	v_fma_f32 v13, v13, v149, v135
	v_mul_f32_e32 v12, v12, v192
	v_mul_f32_e32 v13, v13, v193
	v_lshlrev_b32_e32 v194, 16, v191
	v_and_b32_e32 v195, 0xffff0000, v191
	v_fma_f32 v14, v14, v150, v135
	v_fma_f32 v15, v15, v151, v135
	v_mul_f32_e32 v14, v14, v194
	v_mul_f32_e32 v15, v15, v195
	v_cvt_pk_bf16_f32 v12, v12, v13
	v_cvt_pk_bf16_f32 v13, v14, v15
	global_store_dwordx2 v[156:157], v[12:13], off offset:48
	s_barrier
	s_cbranch_scc1 .LBB0_1061
